# v102 + MLA half-tile stagger of SIMD partners: waves 4-7 take the odd-tile barrier at the end of the tile and fetch the next K half after it
# speedup vs baseline: 1.0011x; 1.0011x over previous
.Lmla_fast_prio:
	s_and_b32 s8, s30, 3
	s_mulk_i32 s8, 0x6400
	s_add_i32 s8, s8, 0
	v_add3_u32 v142, s8, v144, v145
	v_add3_u32 v0, s8, v143, v132
	ds_read_b128 v[194:197], v0
	ds_read_b128 v[150:153], v0 offset:32
	ds_read_b128 v[158:161], v0 offset:64
	ds_read_b128 v[162:165], v0 offset:96
	ds_read_b128 v[174:177], v0 offset:128
	ds_read_b128 v[178:181], v0 offset:160
	s_cmp_lt_u32 s5, 0x1000
	s_cbranch_scc1 .Lmla_fast_grpA
	s_bitcmp1_b32 s30, 0
	s_cbranch_scc1 .Lmla_fast_havek_oB
	s_branch .Lmla_fast_havek_eB
.Lmla_fast_grpA:
	s_bitcmp1_b32 s30, 0
	s_cbranch_scc1 .Lmla_fast_havek_o

.Lmla_fast_needk_eB:
	ds_read_b128 v[194:197], v0
	ds_read_b128 v[150:153], v0 offset:32
	ds_read_b128 v[158:161], v0 offset:64
	ds_read_b128 v[162:165], v0 offset:96
	ds_read_b128 v[174:177], v0 offset:128
	ds_read_b128 v[178:181], v0 offset:160

.Lmla_fast_havek_oB:
.Lmla_fast_nodma_oB:
	s_waitcnt lgkmcnt(0)
	v_mfma_f32_32x32x16_bf16 v[50:65], v[194:197], v[74:77], v[234:249]
	ds_read_b128 v[194:197], v0 offset:6656
	v_add_f32_e32 v254, v202, v203
	v_add_f32_e32 v255, v204, v205
	v_add_f32_e32 v254, v254, v206
	v_add_f32_e32 v255, v255, v207
	v_add_f32_e32 v254, v254, v208
	v_add_f32_e32 v255, v255, v209
	v_mfma_f32_32x32x16_bf16 v[50:65], v[150:153], v[78:81], v[50:65]
	ds_read_b128 v[150:153], v0 offset:6688
	v_add_f32_e32 v254, v254, v210
	v_add_f32_e32 v255, v255, v211
	v_add_f32_e32 v254, v254, v212
	v_add_f32_e32 v255, v255, v213
	v_add_f32_e32 v254, v254, v214
	v_add_f32_e32 v255, v255, v215
	v_mfma_f32_32x32x16_bf16 v[50:65], v[158:161], v[82:85], v[50:65]
	ds_read_b128 v[158:161], v0 offset:6720
	v_add_f32_e32 v254, v254, v216
	v_add_f32_e32 v255, v255, v217
	v_add_f32_e32 v254, v254, v218
	v_add_f32_e32 v255, v255, v219
	v_add_f32_e32 v254, v254, v220
	v_mfma_f32_32x32x16_bf16 v[50:65], v[162:165], v[86:89], v[50:65]
	ds_read_b128 v[162:165], v0 offset:6752
	v_add_f32_e32 v255, v255, v221
	v_add_f32_e32 v254, v254, v222
	v_add_f32_e32 v255, v255, v223
	v_add_f32_e32 v254, v254, v224
	v_add_f32_e32 v255, v255, v225
	v_mfma_f32_32x32x16_bf16 v[50:65], v[174:177], v[90:93], v[50:65]
	ds_read_b128 v[174:177], v0 offset:6784
	v_add_f32_e32 v254, v254, v226
	v_add_f32_e32 v255, v255, v227
	v_add_f32_e32 v254, v254, v228
	v_add_f32_e32 v255, v255, v229
	v_add_f32_e32 v254, v254, v230
	v_mfma_f32_32x32x16_bf16 v[50:65], v[178:181], v[94:97], v[50:65]
	ds_read_b128 v[178:181], v0 offset:6816
	v_add_f32_e32 v255, v255, v231
	v_add_f32_e32 v254, v254, v232
	v_add_f32_e32 v255, v255, v233
	v_add_f32_e32 v254, v254, v255
	v_add_f32_e32 v147, v147, v254
	v_cmp_lt_f32_e32 vcc, 0x44800000, v254
	s_waitcnt lgkmcnt(5)
	v_mfma_f32_32x32x16_bf16 v[34:49], v[194:197], v[74:77], v[234:249]
	ds_read_b64_tr_b16 v[126:127], v142 offset:13312
	ds_read_b64_tr_b16 v[128:129], v142 offset:14848
	ds_read_b64_tr_b16 v[124:125], v142 offset:14912
	ds_read_b64_tr_b16 v[122:123], v142 offset:13376
	s_waitcnt lgkmcnt(8)
	v_mfma_f32_32x32x16_bf16 v[34:49], v[150:153], v[78:81], v[34:49]
	ds_read_b64_tr_b16 v[118:119], v142 offset:16384
	ds_read_b64_tr_b16 v[120:121], v142 offset:17920
	ds_read_b64_tr_b16 v[116:117], v142 offset:17984
	ds_read_b64_tr_b16 v[114:115], v142 offset:16448
	v_exp_f32_e32 v202, v50
	v_exp_f32_e32 v203, v51
	v_exp_f32_e32 v204, v52
	s_waitcnt lgkmcnt(11)
	v_mfma_f32_32x32x16_bf16 v[34:49], v[158:161], v[82:85], v[34:49]
	ds_read_b64_tr_b16 v[110:111], v142 offset:19456
	ds_read_b64_tr_b16 v[112:113], v142 offset:20992
	ds_read_b64_tr_b16 v[108:109], v142 offset:21056
	ds_read_b64_tr_b16 v[106:107], v142 offset:19520
	v_exp_f32_e32 v205, v53
	v_exp_f32_e32 v206, v54
	v_exp_f32_e32 v207, v55
	s_waitcnt lgkmcnt(11)
	v_mfma_f32_32x32x16_bf16 v[34:49], v[162:165], v[86:89], v[34:49]
	ds_read_b64_tr_b16 v[102:103], v142 offset:22528
	ds_read_b64_tr_b16 v[104:105], v142 offset:24064
	ds_read_b64_tr_b16 v[100:101], v142 offset:24128
	ds_read_b64_tr_b16 v[98:99], v142 offset:22592
	v_exp_f32_e32 v208, v56
	v_exp_f32_e32 v209, v57
	v_exp_f32_e32 v210, v58
	v_mfma_f32_32x32x16_bf16 v[34:49], v[174:177], v[90:93], v[34:49]
	v_exp_f32_e32 v211, v59
	v_exp_f32_e32 v212, v60
	v_exp_f32_e32 v213, v61
	v_exp_f32_e32 v214, v62
	v_mfma_f32_32x32x16_bf16 v[34:49], v[178:181], v[94:97], v[34:49]
.Lmla_fast_nostag_oB:
	v_exp_f32_e32 v215, v63
	v_exp_f32_e32 v216, v64
	v_exp_f32_e32 v217, v65
	s_cbranch_vccnz .Lmla_fast_rescale_oB
.Lmla_fast_ok_oB:
	v_cvt_pk_bf16_f32 v166, v202, v203
	v_cvt_pk_bf16_f32 v167, v204, v205
	v_cvt_pk_bf16_f32 v168, v206, v207
	v_cvt_pk_bf16_f32 v169, v208, v209
	s_waitcnt lgkmcnt(0)
	s_nop 0
	v_mfma_f32_32x32x16_bf16 v[18:33], v[126:129], v[166:169], v[18:33]
	s_add_i32 s8, s30, 1
	s_and_b32 s8, s8, 3
	s_mulk_i32 s8, 0x6400
	v_add3_u32 v0, s8, v143, v132
	v_add3_u32 v142, s8, v144, v145
	v_mfma_f32_32x32x16_bf16 v[2:17], v[122:125], v[166:169], v[2:17]
	v_cvt_pk_bf16_f32 v170, v210, v211
	v_cvt_pk_bf16_f32 v171, v212, v213
	v_cvt_pk_bf16_f32 v172, v214, v215
	v_cvt_pk_bf16_f32 v173, v216, v217
	v_exp_f32_e32 v218, v34
	v_exp_f32_e32 v219, v35
	v_mfma_f32_32x32x16_bf16 v[18:33], v[118:121], v[170:173], v[18:33]
	v_exp_f32_e32 v220, v36
	v_exp_f32_e32 v221, v37
	v_mfma_f32_32x32x16_bf16 v[2:17], v[114:117], v[170:173], v[2:17]
	v_exp_f32_e32 v222, v38
	v_exp_f32_e32 v223, v39
	v_exp_f32_e32 v224, v40
	v_exp_f32_e32 v225, v41
	v_cvt_pk_bf16_f32 v166, v218, v219
	v_cvt_pk_bf16_f32 v167, v220, v221
	v_cvt_pk_bf16_f32 v168, v222, v223
	v_cvt_pk_bf16_f32 v169, v224, v225
	s_nop 1
	v_mfma_f32_32x32x16_bf16 v[18:33], v[110:113], v[166:169], v[18:33]
	v_exp_f32_e32 v226, v42
	v_exp_f32_e32 v227, v43
	v_exp_f32_e32 v228, v44
	v_mfma_f32_32x32x16_bf16 v[2:17], v[106:109], v[166:169], v[2:17]
	v_exp_f32_e32 v229, v45
	v_exp_f32_e32 v230, v46
	v_exp_f32_e32 v231, v47
	v_exp_f32_e32 v232, v48
	v_exp_f32_e32 v233, v49
	v_cvt_pk_bf16_f32 v170, v226, v227
	v_cvt_pk_bf16_f32 v171, v228, v229
	v_cvt_pk_bf16_f32 v172, v230, v231
	v_cvt_pk_bf16_f32 v173, v232, v233
	s_add_i32 s30, s30, 1
	s_add_i32 s31, s31, 64
	s_cmp_le_u32 s31, s4
	v_mfma_f32_32x32x16_bf16 v[18:33], v[102:105], v[170:173], v[18:33]
	v_mfma_f32_32x32x16_bf16 v[2:17], v[98:101], v[170:173], v[2:17]
	s_waitcnt vmcnt(0) lgkmcnt(0)
	s_barrier
	s_cbranch_scc1 .Lmla_fast_needk_eB
	s_branch .Lmla_fast_generic
